# mix phase: two 6-hop LDS bpermute wave sums per token replaced by DPP + permlane16/32 swap all-reduce
# speedup vs baseline: 1.0020x; 1.0020x over previous
.LBB0_1120:
	s_waitcnt vmcnt(4)
	v_lshl_add_u64 v[32:33], v[28:29], 0, v[16:17]
	global_load_dwordx4 v[0:3], v[18:19], off offset:48
	global_load_dwordx4 v[4:7], v[18:19], off offset:32
	global_load_dwordx4 v[8:11], v[18:19], off offset:16
	global_load_dwordx4 v[12:15], v[18:19], off
	global_load_dwordx4 v[48:51], v[32:33], off
	global_load_dwordx4 v[52:55], v[32:33], off offset:16
	v_add_co_u32_e32 v34, vcc, s1, v22
	v_lshl_add_u64 v[38:39], v[24:25], 0, v[16:17]
	s_nop 0
	v_addc_co_u32_e32 v35, vcc, 0, v23, vcc
	v_add_co_u32_e32 v36, vcc, s3, v22
	v_add_u32_e32 v47, s80, v47
	s_nop 0
	v_addc_co_u32_e32 v37, vcc, 0, v23, vcc
	v_add_co_u32_e32 v72, vcc, s6, v38
	v_lshl_add_u64 v[30:31], v[26:27], 0, v[16:17]
	s_nop 0
	v_addc_co_u32_e32 v73, vcc, 0, v39, vcc
	v_add_co_u32_e32 v76, vcc, s7, v38
	v_lshl_add_u64 v[32:33], v[38:39], 0, s[20:21]
	s_nop 0
	v_addc_co_u32_e32 v77, vcc, 0, v39, vcc
	v_cmp_lt_i32_e32 vcc, s24, v47
	s_or_b64 s[18:19], vcc, s[18:19]
	v_lshl_add_u64 v[74:75], v[38:39], 0, s[22:23]
	v_lshl_add_u64 v[24:25], v[24:25], 0, s[14:15]
	v_lshl_add_u64 v[26:27], v[26:27], 0, s[16:17]
	v_lshl_add_u64 v[28:29], v[28:29], 0, s[14:15]
	s_waitcnt vmcnt(1)
	v_lshlrev_b32_e32 v56, 16, v48
	v_and_b32_e32 v57, 0xffff0000, v48
	v_lshlrev_b32_e32 v48, 16, v49
	v_and_b32_e32 v49, 0xffff0000, v49
	s_waitcnt vmcnt(0)
	v_lshlrev_b32_e32 v60, 16, v52
	v_and_b32_e32 v61, 0xffff0000, v52
	v_lshlrev_b32_e32 v52, 16, v53
	v_and_b32_e32 v53, 0xffff0000, v53
	v_lshlrev_b32_e32 v62, 16, v54
	v_and_b32_e32 v63, 0xffff0000, v54
	v_lshlrev_b32_e32 v54, 16, v55
	v_and_b32_e32 v55, 0xffff0000, v55
	v_lshlrev_b32_e32 v58, 16, v50
	v_and_b32_e32 v59, 0xffff0000, v50
	v_mov_b32_e32 v66, v63
	v_mov_b32_e32 v67, v55
	v_mov_b32_e32 v70, v61
	v_mov_b32_e32 v71, v53
	v_pk_mul_f32 v[82:83], v[48:49], v[48:49]
	v_pk_mul_f32 v[84:85], v[56:57], v[56:57]
	v_lshlrev_b32_e32 v50, 16, v51
	v_and_b32_e32 v51, 0xffff0000, v51
	v_mov_b32_e32 v64, v62
	v_mov_b32_e32 v65, v54
	v_mov_b32_e32 v68, v60
	v_mov_b32_e32 v69, v52
	v_pk_mul_f32 v[80:81], v[58:59], v[58:59]
	v_pk_mul_f32 v[66:67], v[66:67], v[66:67]
	v_pk_mul_f32 v[70:71], v[70:71], v[70:71]
	v_add_f32_e32 v82, v82, v83
	v_add_f32_e32 v83, v84, v85
	v_pk_mul_f32 v[78:79], v[50:51], v[50:51]
	v_add_f32_e32 v80, v80, v81
	v_pk_fma_f32 v[64:65], v[64:65], v[64:65], v[66:67]
	v_pk_fma_f32 v[66:67], v[68:69], v[68:69], v[70:71]
	v_add_f32_e32 v68, v83, v82
	v_add_f32_e32 v78, v78, v79
	v_add_f32_e32 v68, v68, v80
	v_add_f32_e32 v68, v68, v78
	v_add_f32_e32 v66, v68, v66
	v_add_f32_e32 v66, v66, v67
	v_add_f32_e32 v64, v66, v64
	v_add_f32_e32 v64, v64, v65
	s_nop 1
	v_add_f32_dpp v64, v64, v64 quad_perm:[1,0,3,2] row_mask:0xf bank_mask:0xf
	s_nop 1
	v_add_f32_dpp v64, v64, v64 quad_perm:[2,3,0,1] row_mask:0xf bank_mask:0xf
	s_nop 1
	v_add_f32_dpp v64, v64, v64 row_half_mirror row_mask:0xf bank_mask:0xf
	s_nop 1
	v_add_f32_dpp v64, v64, v64 row_mirror row_mask:0xf bank_mask:0xf
	s_nop 1
	v_mov_b32_e32 v65, v64
	s_nop 1
	v_permlane16_swap_b32 v65, v64
	v_add_f32_e32 v64, v64, v65
	v_mov_b32_e32 v65, v64
	s_nop 1
	v_permlane32_swap_b32 v65, v64
	v_add_f32_e32 v64, v64, v65
	v_fmamk_f32 v64, v64, 0x3a800000, v46
	v_mul_f32_e32 v65, 0x4b800000, v64
	v_cmp_gt_f32_e32 vcc, s0, v64
	s_nop 1
	v_cndmask_b32_e32 v64, v64, v65, vcc
	v_rsq_f32_e32 v64, v64
	s_nop 0
	v_mul_f32_e32 v65, 0x45800000, v64
	v_cndmask_b32_e32 v64, v64, v65, vcc
	v_pk_mul_f32 v[56:57], v[64:65], v[56:57] op_sel_hi:[0,1]
	v_pk_mul_f32 v[48:49], v[64:65], v[48:49] op_sel_hi:[0,1]
	v_pk_mul_f32 v[58:59], v[64:65], v[58:59] op_sel_hi:[0,1]
	v_pk_mul_f32 v[50:51], v[64:65], v[50:51] op_sel_hi:[0,1]
	v_pk_mul_f32 v[60:61], v[64:65], v[60:61] op_sel_hi:[0,1]
	v_pk_mul_f32 v[52:53], v[64:65], v[52:53] op_sel_hi:[0,1]
	v_pk_mul_f32 v[62:63], v[64:65], v[62:63] op_sel_hi:[0,1]
	v_pk_mul_f32 v[54:55], v[64:65], v[54:55] op_sel_hi:[0,1]
	v_pk_mul_f32 v[12:13], v[12:13], v[56:57]
	v_pk_mul_f32 v[14:15], v[14:15], v[48:49]
	v_pk_mul_f32 v[8:9], v[8:9], v[58:59]
	v_pk_mul_f32 v[10:11], v[10:11], v[50:51]
	v_pk_mul_f32 v[4:5], v[4:5], v[60:61]
	v_pk_mul_f32 v[6:7], v[6:7], v[52:53]
	v_pk_mul_f32 v[48:49], v[62:63], v[0:1]
	v_pk_mul_f32 v[50:51], v[54:55], v[2:3]
	v_cvt_pk_bf16_f32 v0, v12, v13
	v_cvt_pk_bf16_f32 v1, v14, v15
	v_cvt_pk_bf16_f32 v2, v8, v9
	v_cvt_pk_bf16_f32 v3, v10, v11
	v_cvt_pk_bf16_f32 v4, v4, v5
	v_cvt_pk_bf16_f32 v5, v6, v7
	v_cvt_pk_bf16_f32 v6, v48, v49
	v_cvt_pk_bf16_f32 v7, v50, v51
	global_store_dwordx4 v[30:31], v[0:3], off
	global_store_dwordx4 v[30:31], v[4:7], off offset:16
	global_load_dword v88, v[22:23], off
	global_load_dword v89, v[34:35], off
	global_load_dword v90, v[36:37], off
	s_nop 0
	global_load_dwordx4 v[0:3], v[38:39], off
	global_load_dwordx4 v[4:7], v[38:39], off offset:16
	global_load_dwordx4 v[8:11], v[72:73], off
	global_load_dwordx4 v[12:15], v[32:33], off offset:16
	global_load_dwordx4 v[48:51], v[76:77], off
	global_load_dwordx4 v[52:55], v[74:75], off offset:16
	global_load_dwordx4 v[56:59], v[20:21], off offset:48
	global_load_dwordx4 v[60:63], v[20:21], off offset:32
	global_load_dwordx4 v[64:67], v[20:21], off offset:16
	global_load_dwordx4 v[68:71], v[20:21], off
	v_lshl_add_u64 v[22:23], v[22:23], 0, s[12:13]
	s_waitcnt vmcnt(10)
	v_max3_f32 v91, v88, v89, v90
	v_sub_f32_e32 v88, v88, v91
	v_sub_f32_e32 v89, v89, v91
	v_sub_f32_e32 v90, v90, v91
	v_exp_f32_e32 v88, v88
	v_exp_f32_e32 v89, v89
	v_exp_f32_e32 v91, v90
	s_waitcnt vmcnt(9)
	v_lshlrev_b32_e32 v32, 16, v0
	v_and_b32_e32 v33, 0xffff0000, v0
	v_add_f32_e32 v90, v88, v89
	v_add_f32_e32 v90, v91, v90
	v_div_scale_f32 v92, s[26:27], v90, v90, 1.0
	v_rcp_f32_e32 v94, v92
	v_div_scale_f32 v93, vcc, 1.0, v90, 1.0
	v_lshlrev_b32_e32 v0, 16, v1
	v_fma_f32 v95, -v92, v94, 1.0
	v_fmac_f32_e32 v94, v95, v94
	v_mul_f32_e32 v95, v93, v94
	v_fma_f32 v96, -v92, v95, v93
	v_fmac_f32_e32 v95, v96, v94
	v_fma_f32 v92, -v92, v95, v93
	v_div_fmas_f32 v92, v92, v94, v95
	v_div_fixup_f32 v92, v92, v90, 1.0
	v_and_b32_e32 v1, 0xffff0000, v1
	v_mul_f32_e32 v88, v88, v92
	s_waitcnt vmcnt(8)
	v_lshlrev_b32_e32 v38, 16, v6
	v_and_b32_e32 v39, 0xffff0000, v6
	v_lshlrev_b32_e32 v6, 16, v7
	v_and_b32_e32 v7, 0xffff0000, v7
	s_waitcnt vmcnt(7)
	v_lshlrev_b32_e32 v72, 16, v8
	v_and_b32_e32 v73, 0xffff0000, v8
	v_lshlrev_b32_e32 v8, 16, v9
	v_and_b32_e32 v9, 0xffff0000, v9
	v_mul_f32_e32 v90, v89, v92
	v_pk_fma_f32 v[0:1], v[88:89], v[0:1], 0 op_sel_hi:[0,1,0]
	v_pk_fma_f32 v[32:33], v[88:89], v[32:33], 0 op_sel_hi:[0,1,0]
	v_lshlrev_b32_e32 v36, 16, v4
	v_and_b32_e32 v37, 0xffff0000, v4
	v_lshlrev_b32_e32 v4, 16, v5
	v_and_b32_e32 v5, 0xffff0000, v5
	s_waitcnt vmcnt(6)
	v_lshlrev_b32_e32 v78, 16, v14
	v_and_b32_e32 v79, 0xffff0000, v14
	v_lshlrev_b32_e32 v14, 16, v15
	v_and_b32_e32 v15, 0xffff0000, v15
	s_waitcnt vmcnt(5)
	v_lshlrev_b32_e32 v80, 16, v48
	v_and_b32_e32 v81, 0xffff0000, v48
	v_mul_f32_e32 v92, v91, v92
	v_pk_fma_f32 v[6:7], v[88:89], v[6:7], 0 op_sel_hi:[0,1,0]
	v_pk_fma_f32 v[0:1], v[90:91], v[8:9], v[0:1] op_sel_hi:[0,1,1]
	v_pk_fma_f32 v[8:9], v[90:91], v[72:73], v[32:33] op_sel_hi:[0,1,1]
	v_lshlrev_b32_e32 v34, 16, v2
	v_and_b32_e32 v35, 0xffff0000, v2
	v_lshlrev_b32_e32 v2, 16, v3
	v_and_b32_e32 v3, 0xffff0000, v3
	v_lshlrev_b32_e32 v76, 16, v12
	v_and_b32_e32 v77, 0xffff0000, v12
	v_lshlrev_b32_e32 v12, 16, v13
	v_and_b32_e32 v13, 0xffff0000, v13
	v_lshlrev_b32_e32 v48, 16, v49
	v_and_b32_e32 v49, 0xffff0000, v49
	s_waitcnt vmcnt(4)
	v_lshlrev_b32_e32 v86, 16, v54
	v_and_b32_e32 v87, 0xffff0000, v54
	v_lshlrev_b32_e32 v54, 16, v55
	v_and_b32_e32 v55, 0xffff0000, v55
	v_pk_fma_f32 v[4:5], v[88:89], v[4:5], 0 op_sel_hi:[0,1,0]
	v_pk_fma_f32 v[6:7], v[90:91], v[14:15], v[6:7] op_sel_hi:[0,1,1]
	v_pk_fma_f32 v[8:9], v[92:93], v[80:81], v[8:9] op_sel_hi:[0,1,1]
	v_lshlrev_b32_e32 v74, 16, v10
	v_and_b32_e32 v75, 0xffff0000, v10
	v_lshlrev_b32_e32 v10, 16, v11
	v_and_b32_e32 v11, 0xffff0000, v11
	v_lshlrev_b32_e32 v84, 16, v52
	v_and_b32_e32 v85, 0xffff0000, v52
	v_lshlrev_b32_e32 v52, 16, v53
	v_and_b32_e32 v53, 0xffff0000, v53
	v_pk_fma_f32 v[2:3], v[88:89], v[2:3], 0 op_sel_hi:[0,1,0]
	v_pk_fma_f32 v[34:35], v[88:89], v[34:35], 0 op_sel_hi:[0,1,0]
	v_pk_fma_f32 v[4:5], v[90:91], v[12:13], v[4:5] op_sel_hi:[0,1,1]
	v_pk_fma_f32 v[6:7], v[92:93], v[54:55], v[6:7] op_sel_hi:[0,1,1]
	v_pk_fma_f32 v[0:1], v[92:93], v[48:49], v[0:1] op_sel_hi:[0,1,1]
	v_pk_mul_f32 v[54:55], v[8:9], v[8:9]
	v_lshlrev_b32_e32 v82, 16, v50
	v_and_b32_e32 v83, 0xffff0000, v50
	v_pk_fma_f32 v[2:3], v[90:91], v[10:11], v[2:3] op_sel_hi:[0,1,1]
	v_pk_fma_f32 v[10:11], v[90:91], v[74:75], v[34:35] op_sel_hi:[0,1,1]
	v_pk_fma_f32 v[4:5], v[92:93], v[52:53], v[4:5] op_sel_hi:[0,1,1]
	v_pk_mul_f32 v[52:53], v[0:1], v[0:1]
	v_add_f32_e32 v54, v54, v55
	v_lshlrev_b32_e32 v50, 16, v51
	v_and_b32_e32 v51, 0xffff0000, v51
	v_pk_fma_f32 v[10:11], v[92:93], v[82:83], v[10:11] op_sel_hi:[0,1,1]
	v_add_f32_e32 v52, v54, v52
	v_pk_fma_f32 v[2:3], v[92:93], v[50:51], v[2:3] op_sel_hi:[0,1,1]
	v_pk_mul_f32 v[50:51], v[10:11], v[10:11]
	v_add_f32_e32 v52, v53, v52
	v_pk_fma_f32 v[36:37], v[88:89], v[36:37], 0 op_sel_hi:[0,1,0]
	v_add_f32_e32 v50, v50, v52
	v_pk_fma_f32 v[12:13], v[90:91], v[76:77], v[36:37] op_sel_hi:[0,1,1]
	v_pk_mul_f32 v[48:49], v[2:3], v[2:3]
	v_add_f32_e32 v50, v51, v50
	v_pk_fma_f32 v[38:39], v[88:89], v[38:39], 0 op_sel_hi:[0,1,0]
	v_pk_fma_f32 v[12:13], v[92:93], v[84:85], v[12:13] op_sel_hi:[0,1,1]
	v_add_f32_e32 v48, v48, v50
	v_pk_fma_f32 v[14:15], v[90:91], v[78:79], v[38:39] op_sel_hi:[0,1,1]
	v_pk_mul_f32 v[38:39], v[12:13], v[12:13]
	v_add_f32_e32 v48, v49, v48
	v_add_f32_e32 v38, v38, v48
	v_pk_mul_f32 v[36:37], v[4:5], v[4:5]
	v_add_f32_e32 v38, v39, v38
	v_pk_fma_f32 v[14:15], v[92:93], v[86:87], v[14:15] op_sel_hi:[0,1,1]
	v_add_f32_e32 v36, v36, v38
	v_pk_mul_f32 v[34:35], v[14:15], v[14:15]
	v_add_f32_e32 v36, v37, v36
	v_add_f32_e32 v34, v34, v36
	v_pk_mul_f32 v[32:33], v[6:7], v[6:7]
	v_add_f32_e32 v34, v35, v34
	v_add_f32_e32 v32, v32, v34
	v_add_f32_e32 v32, v33, v32
	s_nop 1
	v_add_f32_dpp v32, v32, v32 quad_perm:[1,0,3,2] row_mask:0xf bank_mask:0xf
	s_nop 1
	v_add_f32_dpp v32, v32, v32 quad_perm:[2,3,0,1] row_mask:0xf bank_mask:0xf
	s_nop 1
	v_add_f32_dpp v32, v32, v32 row_half_mirror row_mask:0xf bank_mask:0xf
	s_nop 1
	v_add_f32_dpp v32, v32, v32 row_mirror row_mask:0xf bank_mask:0xf
	s_nop 1
	v_mov_b32_e32 v33, v32
	s_nop 1
	v_permlane16_swap_b32 v33, v32
	v_add_f32_e32 v32, v32, v33
	v_mov_b32_e32 v33, v32
	s_nop 1
	v_permlane32_swap_b32 v33, v32
	v_add_f32_e32 v32, v32, v33
	v_fmamk_f32 v32, v32, 0x3a800000, v46
	v_mul_f32_e32 v33, 0x4b800000, v32
	v_cmp_gt_f32_e32 vcc, s0, v32
	s_nop 1
	v_cndmask_b32_e32 v32, v32, v33, vcc
	v_rsq_f32_e32 v32, v32
	s_nop 0
	v_mul_f32_e32 v33, 0x45800000, v32
	v_cndmask_b32_e32 v32, v32, v33, vcc
	v_pk_mul_f32 v[8:9], v[8:9], v[32:33] op_sel_hi:[1,0]
	v_pk_mul_f32 v[0:1], v[0:1], v[32:33] op_sel_hi:[1,0]
	v_pk_mul_f32 v[10:11], v[10:11], v[32:33] op_sel_hi:[1,0]
	v_pk_mul_f32 v[2:3], v[2:3], v[32:33] op_sel_hi:[1,0]
	v_pk_mul_f32 v[12:13], v[12:13], v[32:33] op_sel_hi:[1,0]
	v_pk_mul_f32 v[4:5], v[4:5], v[32:33] op_sel_hi:[1,0]
	v_pk_mul_f32 v[14:15], v[14:15], v[32:33] op_sel_hi:[1,0]
	v_pk_mul_f32 v[6:7], v[6:7], v[32:33] op_sel_hi:[1,0]
	s_waitcnt vmcnt(0)
	v_pk_mul_f32 v[8:9], v[68:69], v[8:9]
	v_pk_mul_f32 v[32:33], v[70:71], v[0:1]
	v_pk_mul_f32 v[10:11], v[64:65], v[10:11]
	v_pk_mul_f32 v[34:35], v[66:67], v[2:3]
	v_pk_mul_f32 v[12:13], v[60:61], v[12:13]
	v_pk_mul_f32 v[36:37], v[62:63], v[4:5]
	v_pk_mul_f32 v[14:15], v[56:57], v[14:15]
	v_pk_mul_f32 v[38:39], v[58:59], v[6:7]
	v_cvt_pk_bf16_f32 v0, v8, v9
	v_cvt_pk_bf16_f32 v1, v32, v33
	v_cvt_pk_bf16_f32 v2, v10, v11
	v_cvt_pk_bf16_f32 v3, v34, v35
	v_cvt_pk_bf16_f32 v4, v12, v13
	v_cvt_pk_bf16_f32 v5, v36, v37
	v_cvt_pk_bf16_f32 v6, v14, v15
	v_cvt_pk_bf16_f32 v7, v38, v39
	global_store_dwordx4 v[30:31], v[0:3], off offset:2048
	global_store_dwordx4 v[30:31], v[4:7], off offset:2064
	s_andn2_b64 exec, exec, s[18:19]
	s_cbranch_execnz .LBB0_1120
